# stack10 + attention prologue QK^T: the 7 remaining K fragments requested up front (counted lgkmcnt) instead of 7 exposed LDS round trips
# baseline (speedup 1.0000x reference)
; __device__ __forceinline__ void qkt(f32x16& p0, f32x16& p1, const char* Kslot, const s16x8* qr, const f32x16& negm, int r32, int hi) {
;   const char* kb = Kslot + hi * 1024 + r32 * 16;
; #pragma unroll
;   for (int d0 = 0; d0 < 4; ++d0) {
;     const s16x8 b0 = *reinterpret_cast<const s16x8*>(kb + d0 * 2048);
;     const s16x8 b1 = *reinterpret_cast<const s16x8*>(kb + d0 * 2048 + 512);
;     if (d0 == 0) { p0 = __builtin_amdgcn_mfma_f32_32x32x16_f16(H8(b0), H8(qr[0]), negm, 0, 0, 0); p1 = __builtin_amdgcn_mfma_f32_32x32x16_f16(H8(b1), H8(qr[0]), negm, 0, 0, 0); }
;     else { p0 = __builtin_amdgcn_mfma_f32_32x32x16_f16(H8(b0), H8(qr[d0]), p0, 0, 0, 0); p1 = __builtin_amdgcn_mfma_f32_32x32x16_f16(H8(b1), H8(qr[d0]), p1, 0, 0, 0); } }
; }
.Lat_warm_join:
	ds_read_b128 v[192:195], v219 offset:512
	ds_read_b128 v[188:191], v219 offset:2048
	ds_read_b128 v[184:187], v219 offset:2560
	ds_read_b128 v[180:183], v219 offset:4096
	ds_read_b128 v[176:179], v219 offset:4608
	ds_read_b128 v[172:175], v219 offset:6144
	ds_read_b128 v[168:171], v219 offset:6656
	v_mfma_f32_32x32x16_f16 v[18:33], v[38:41], v[144:147], v[2:17]
	s_waitcnt lgkmcnt(6)
	v_mfma_f32_32x32x16_f16 v[2:17], v[192:195], v[144:147], v[2:17]
	s_waitcnt lgkmcnt(5)
	v_mfma_f32_32x32x16_f16 v[18:33], v[188:191], v[140:143], v[18:33]
	s_waitcnt lgkmcnt(4)
	v_mfma_f32_32x32x16_f16 v[2:17], v[184:187], v[140:143], v[2:17]
	s_waitcnt lgkmcnt(3)
	v_mfma_f32_32x32x16_f16 v[18:33], v[180:183], v[136:139], v[18:33]
	s_waitcnt lgkmcnt(2)
	v_mfma_f32_32x32x16_f16 v[2:17], v[176:179], v[136:139], v[2:17]
	s_waitcnt lgkmcnt(1)
	v_mfma_f32_32x32x16_f16 v[18:33], v[172:175], v[132:135], v[18:33]
	s_waitcnt lgkmcnt(0)
	v_mfma_f32_32x32x16_f16 v[2:17], v[168:171], v[132:135], v[2:17]
	s_nop 15
	s_nop 7
	s_nop 0
	v_sub_f32_e32 v0, v2, v53
	s_nop 10
	v_xor_b32_e32 v2, 0x80000000, v54
	v_sub_f32_e32 v38, v18, v53
	v_sub_f32_e32 v39, v19, v53
	v_sub_f32_e32 v18, v3, v53
	v_sub_f32_e32 v40, v20, v53
	v_sub_f32_e32 v19, v4, v53
	v_sub_f32_e32 v41, v21, v53
	v_sub_f32_e32 v20, v5, v53
	v_sub_f32_e32 v42, v22, v53
	v_sub_f32_e32 v21, v6, v53
	v_sub_f32_e32 v43, v23, v53
	v_sub_f32_e32 v22, v7, v53
	v_sub_f32_e32 v44, v24, v53
	v_sub_f32_e32 v23, v8, v53
	v_sub_f32_e32 v45, v25, v53
	v_sub_f32_e32 v24, v9, v53
	v_sub_f32_e32 v46, v26, v53
	v_sub_f32_e32 v25, v10, v53
	v_sub_f32_e32 v47, v27, v53
	v_sub_f32_e32 v26, v11, v53
	v_sub_f32_e32 v48, v28, v53
	v_sub_f32_e32 v27, v12, v53
	v_sub_f32_e32 v49, v29, v53
	v_sub_f32_e32 v28, v13, v53
	v_sub_f32_e32 v50, v30, v53
	v_sub_f32_e32 v29, v14, v53
	v_sub_f32_e32 v51, v31, v53
	v_sub_f32_e32 v30, v15, v53
	v_sub_f32_e32 v52, v32, v53
	v_sub_f32_e32 v31, v16, v53
	v_sub_f32_e32 v32, v17, v53
	v_mov_b32_e32 v3, v2
	v_mov_b32_e32 v4, v2
	v_mov_b32_e32 v5, v2
	v_mov_b32_e32 v6, v2
	v_mov_b32_e32 v7, v2
	v_mov_b32_e32 v8, v2
	v_mov_b32_e32 v9, v2
	v_mov_b32_e32 v10, v2
	v_mov_b32_e32 v11, v2
	v_mov_b32_e32 v12, v2
	v_mov_b32_e32 v13, v2
	v_mov_b32_e32 v14, v2
	v_mov_b32_e32 v15, v2
	v_mov_b32_e32 v16, v2
	v_mov_b32_e32 v17, v2
	v_sub_f32_e32 v33, v33, v53
	s_cbranch_vccnz .LBB0_73
	s_waitcnt vmcnt(0) lgkmcnt(0)
	s_barrier
	s_mov_b64 s[2:3], 0
